# + m22: scan_item items renumbered so a segment runs on the XCD owning its tokens; the scan_item->W_a/W_b barrier becomes XCD-local without L2 write-back (invalidate kept); same placement guard
# speedup vs baseline: 1.0085x; 1.0049x over previous
; #define LAS __attribute__((address_space(3)))
; template <bool OUT>
; __device__ __forceinline__ void scan_item(LAS unsigned char* lds, unsigned char* ws, const float* hgn_l, int item, int tid_in, int wid, int lane_in) {
;     const int h = item / NSEG, seg = item % NSEG;
;     float* SEG = (float*)(ws + WS_SEG); float* DSEG = (float*)(ws + WS_DSEG);
;     const bf16* Qp = (const bf16*)(ws + WS_Q); const bf16* Vp = (const bf16*)(ws + WS_V); bf16* AOp = (bf16*)(ws + WS_AO); const bf16* ZGp = (const bf16*)(ws + WS_ZG);
;     LAS unsigned short* QD = (LAS unsigned short*)(lds + L_QD); LAS unsigned short* QS = (LAS unsigned short*)(lds + L_QS); LAS unsigned short* KS = (LAS unsigned short*)(lds + L_KS);
;     LAS float* TOT = (LAS float*)(lds + L_TOT); LAS float* DV = (LAS float*)(lds + L_DV); LAS float* RS = (LAS float*)(lds + L_RS);
;     for (int dir = 0; dir < 2; ++dir) {
;         if (OUT && dir == 1) __syncthreads();
;         int tid = tid_in, lane = lane_in;
;         asm volatile("" : "+v"(tid), "+v"(lane));
;         f32x16 S[2];
;         bf16* spb = (bf16*)SEG + (size_t)((h * 2 + dir) * NSEG + seg) * 16384;
;         {
;             const int r = lane & 31, hh = lane >> 5, kb = wid >> 1;
; #pragma unroll
;             for (int j = 0; j < 2; ++j) { const int vc = (2 * (wid & 1) + j) * 32 + r;
; #pragma unroll
;                 for (int g = 0; g < 4; ++g) {
;                     if (OUT) { const u32x2 w = *(const u32x2*)(spb + vc * 128 + kb * 32 + 8 * g + 4 * hh);
;                         S[j][4 * g] = __uint_as_float(w.x << 16); S[j][4 * g + 1] = __uint_as_float(w.x & 0xffff0000u); S[j][4 * g + 2] = __uint_as_float(w.y << 16); S[j][4 * g + 3] = __uint_as_float(w.y & 0xffff0000u); }
;                     else { S[j][4 * g] = 0.f; S[j][4 * g + 1] = 0.f; S[j][4 * g + 2] = 0.f; S[j][4 * g + 3] = 0.f; } } }
;         }
;         const unsigned short* LFp = (const unsigned short*)(ws + (dir ? WS_LB : WS_LF));
;         unsigned lraw[8], vraw[8], qraw[8];
;         float dsa = 0.f, dsb = 0.f;
;         const int es = dir ? -D : D;
;         {
;             const int c = seg * SEGCH + (dir ? SEGCH - 1 : 0);
;             const unsigned e0 = (unsigned)((c * 64 + (dir ? 63 - wid * 8 : wid * 8)) * D + h * 128 + 2 * lane);
.LBB0_356:
	s_andn2_b64 vcc, exec, s[6:7]
	s_cbranch_vccnz .LBB0_392
	s_cmpk_gt_i32 s68, 0xff
	s_cbranch_scc1 .LBB0_392
	s_load_dwordx2 s[0:1], s[66:67], 0x30
	s_lshl_b32 s6, s82, 10
	s_ashr_i32 s7, s6, 31
	s_lshl_b64 s[6:7], s[6:7], 2
	v_writelane_b32 v255, s96, 22
	s_waitcnt lgkmcnt(0)
	s_add_u32 s40, s0, s6
	s_addc_u32 s41, s1, s7
	v_writelane_b32 v255, s97, 23
	s_add_u32 s28, s30, 0x8a00000
	v_writelane_b32 v255, s94, 24
	s_addc_u32 s29, s31, 0
	s_add_u32 s78, s30, 0xea00000
	v_writelane_b32 v255, s95, 25
	v_writelane_b32 v255, s92, 26
	s_addc_u32 s79, s31, 0
	s_add_u32 s80, s30, 0x19a00000
	v_writelane_b32 v255, s93, 27
	v_writelane_b32 v255, s91, 28
	s_mov_b32 s2, s82
	s_addc_u32 s81, s31, 0
	v_writelane_b32 v255, s2, 29
	s_add_u32 s82, s30, 0x10a00000
	s_addc_u32 s83, s31, 0
	v_writelane_b32 v255, s3, 30
	s_ashr_i32 s2, s90, 7
	s_lshl_b32 s84, s2, 5
	s_lshl_b32 s0, s69, 1
	s_ashr_i32 s85, s84, 31
	s_and_b32 s8, s0, 2
	s_lshl_b64 s[0:1], s[84:85], 1
	s_add_u32 s0, s30, s0
	s_addc_u32 s1, s31, s1
	s_add_u32 s85, s0, 0x1ba00000
	s_addc_u32 s60, s1, 0
	s_lshl_b32 s0, s2, 6
	s_add_i32 s34, s0, 0
	s_lshl_b32 s0, s69, 9
	s_lshl_b32 s54, s69, 3
	s_add_i32 s35, s0, 0
	s_sub_i32 s55, 63, s54
	s_add_i32 s34, s34, 0x15c00
	s_add_i32 s35, s35, 0x20800
	s_cmp_lt_u32 s90, 64
	s_cselect_b64 s[86:87], -1, 0
	s_lshl_b32 s2, s69, 5
	s_and_b32 s0, s2, 0x60
	s_cmp_lt_i32 s69, 4
	s_cselect_b64 s[88:89], -1, 0
	s_cmp_gt_i32 s69, 3
	s_cselect_b64 s[6:7], -1, 0
	s_and_b32 s1, s90, 0xffffff80
	s_add_i32 s1, s1, 0
	s_add_i32 s1, s1, 0x21800
	s_cmp_lg_u32 s69, 1
	v_writelane_b32 v255, s90, 31
	s_cselect_b64 s[90:91], -1, 0
	s_and_b32 s46, s2, 32
	s_or_b32 s2, s8, 1
	s_and_b32 s47, s54, 0xffffffe0
	s_lshl_b32 s76, s8, 12
	s_lshl_b32 s77, s2, 12
	s_lshl_b32 s71, s8, 5
	s_lshl_b32 s2, s2, 5
	s_cmp_gt_i32 s69, 0
	s_cselect_b64 s[8:9], -1, 0
	s_cmp_gt_i32 s69, 1
	s_cselect_b64 s[10:11], -1, 0
	s_cmp_gt_i32 s69, 2
	s_cselect_b64 s[12:13], -1, 0
	s_cmp_gt_i32 s69, 4
	s_cselect_b64 s[14:15], -1, 0
	s_cmp_gt_i32 s69, 5
	s_cselect_b64 s[16:17], -1, 0
	s_cmp_gt_i32 s69, 6
	s_cselect_b64 s[18:19], -1, 0
	s_cmp_gt_i32 s69, 7
	s_cselect_b64 s[20:21], -1, 0
	s_and_b32 s74, s68, 0xffffffe0
	s_and_b32 s98, s68, 7
	s_lshl_b32 s98, s98, 2
	s_or_b32 s74, s74, s98
	s_lshr_b32 s98, s68, 3
	s_and_b32 s98, s98, 3
	s_or_b32 s74, s74, s98
	s_branch .LBB0_360

; __device__ __forceinline__ unsigned xb_ld(unsigned* p)              { return __hip_atomic_load(p, __ATOMIC_RELAXED, __HIP_MEMORY_SCOPE_AGENT); }
; __device__ __forceinline__ unsigned xb_add(unsigned* p, unsigned v) { return __hip_atomic_fetch_add(p, v, __ATOMIC_RELAXED, __HIP_MEMORY_SCOPE_AGENT); }
; #define XB_SPIN(cond, bar) do { unsigned _sp = 0; while (cond) { __builtin_amdgcn_s_sleep(0); \
;     if ((++_sp & 255u) == 0u) { if (xb_ld(&(bar)[XB_TMO])) break; if (_sp > XB_SPIN_CAP) { atomicAdd(&(bar)[XB_TMO], 1u); break; } } } } while (0)
; __device__ __forceinline__ void xcd_barrier(const XcdBarrier& b) {
;     ...
;         const unsigned old = xb_add(&bar[XB_XSUB(b.x)], 1u);
;         const unsigned gen = old / nloc;
;         if (old + 1u == (gen + 1u) * nloc) {
;             __builtin_amdgcn_fence(__ATOMIC_RELEASE, "agent");
;             asm volatile("s_waitcnt vmcnt(0)" ::: "memory");
;             const unsigned og = xb_add(&bar[XB_TOP], 1u);
;             const unsigned tg = og / nx;
;             if (og + 1u == (tg + 1u) * nx) xb_add(&bar[XB_TOPGEN], 1u);
;             else XB_SPIN(xb_ld(&bar[XB_TOPGEN]) == tg, bar);
;             __builtin_amdgcn_fence(__ATOMIC_ACQUIRE, "agent");
;             xb_add(&bar[XB_XGEN(b.x)], 1u);
;             asm volatile("s_waitcnt vmcnt(0)" ::: "memory");
.LBB0_756:
	s_andn2_saveexec_b64 s[10:11], s[10:11]
	s_cbranch_execz .LBB0_776
	s_mov_b64 s[10:11], exec
	v_readlane_b32 s99, v255, 42
	s_cmp_ge_u32 s3, 18
	s_cselect_b32 s98, 18, 0
	s_sub_u32 s98, s3, s98
	s_cmp_eq_u32 s99, 0
	s_cbranch_scc1 .Lfull_l
	s_cmp_eq_u32 s98, 4
	s_cbranch_scc1 .Lnf_l4
	s_cmp_eq_u32 s98, 10
	s_cbranch_scc1 .Lnf_l4
	s_cmp_eq_u32 s98, 5
	s_cbranch_scc1 .Lnf_l
	s_cmp_eq_u32 s98, 6
	s_cbranch_scc1 .Lnf_l
	s_cmp_eq_u32 s98, 11
	s_cbranch_scc1 .Lnf_l
.Lfull_l:
	buffer_wbl2 sc1
	buffer_inv sc1
	s_branch .Lnf_l2
.Lnf_l4:
	buffer_inv sc1
.Lnf_l:
	s_waitcnt lgkmcnt(0)
	s_branch .LBB0_773
